# DN-PP seams group-scoped with cross-group waits; GATE0-QKV seam also waits for the DN0 readers of the HDN panels its K/V tiles overlay
# baseline (speedup 1.0000x reference)
.Lg7_BB0_1003:
	s_or_b64 exec, exec, s[4:5]
	s_and_b32 s4, s81, 7
	s_lshl_b32 s4, s4, 3
	s_bfe_u32 s5, s81, 0x30003
	s_add_i32 s4, s4, s5
	s_lshr_b32 s12, s4, 2
	s_add_i32 s14, s12, 32
	s_add_i32 s12, s12, 16
	s_mov_b32 s13, 1
	v_mov_b32_e32 v1, 0
	s_mov_b32 s9, 16
	s_mov_b32 s8, 0
